# ph6+ph8: half of the workgroups without a third GEMM unit run the fp4 conversion stream BEFORE their GEMM units (overlaps HBM-bound stream with MFMA-bound units)
# speedup vs baseline: 1.0399x; 1.0187x over previous
.LBB0_1651:
	s_cmp_lt_i32 s94, 7
	s_cselect_b64 s[6:7], -1, 0
	s_and_b64 s[0:1], s[6:7], s[0:1]
	s_andn2_b64 vcc, exec, s[0:1]
	s_cbranch_vccnz .LBB0_1755
	s_mov_b32 s99, 0
	s_cmp_lt_i32 s70, 32
	s_cbranch_scc1 .Lp6_G
	s_bitcmp1_b32 s70, 3
	s_cbranch_scc0 .Lp6_G
	s_mov_b32 s99, 1
	s_load_dword s30, s[68:69], 0xe0
	v_lshrrev_b32_e32 v1, 3, v0
	v_lshlrev_b32_e32 v152, 2, v0
	s_waitcnt lgkmcnt(0)
	s_branch .LBB0_1698
.Lp6_G:
	s_cmpk_lt_i32 s70, 0x220
	s_cselect_b64 s[0:1], -1, 0
	s_cmpk_gt_i32 s70, 0x21f
	v_readfirstlane_b32 s31, v0
	s_cbranch_scc1 .LBB0_1654
	s_ashr_i32 s2, s70, 31
	s_lshr_b32 s2, s2, 29
	s_add_i32 s2, s70, s2
	s_ashr_i32 s3, s2, 3
	s_and_b32 s2, s2, -8
	s_sub_i32 s2, s70, s2
	s_cmp_lt_i32 s2, 0
	s_movk_i32 s4, 0x45
	s_cselect_b32 s4, s4, 0x44
	s_mul_i32 s2, s4, s2
	s_add_i32 s2, s2, s3
	s_ashr_i32 s3, s2, 31
	s_lshr_b32 s3, s3, 26
	s_add_i32 s3, s2, s3
	s_ashr_i32 s4, s3, 6
	s_lshl_b32 s4, s4, 3
	s_sub_i32 s5, 0x44, s4
	s_min_u32 s5, s5, 8
	s_andn2_b32 s3, s3, 63
	s_sub_i32 s8, s2, s3
	v_cvt_f32_ubyte0_e32 v2, s5
	v_cvt_f32_i32_e32 v1, s8
	v_rcp_iflag_f32_e32 v3, v2
	s_ashr_i32 s2, s8, 30
	s_or_b32 s9, s2, 1
	v_mul_f32_e32 v3, v1, v3
	v_trunc_f32_e32 v3, v3
	v_fma_f32 v1, -v3, v2, v1
	v_cvt_i32_f32_e32 v3, v3
	v_cmp_ge_f32_e64 s[2:3], |v1|, v2
	s_and_b64 s[2:3], s[2:3], exec
	s_cselect_b32 s2, s9, 0
	v_readfirstlane_b32 s3, v3
	s_add_i32 s2, s3, s2
	s_sext_i32_i8 s22, s2
	s_mul_i32 s2, s2, s5
	s_sub_i32 s2, s8, s2
	s_sext_i32_i8 s2, s2
	s_add_i32 s2, s4, s2

.LBB0_1698:
	s_cmp_eq_u32 s99, 2
	s_cbranch_scc1 .LBB0_1755
	s_waitcnt lgkmcnt(0)
	s_cmpk_lg_i32 s30, 0x100
	s_cselect_b64 s[0:1], -1, 0
	s_cmp_lt_i32 s70, 32
	s_cselect_b64 s[2:3], -1, 0
	s_or_b64 s[4:5], s[2:3], s[0:1]
	s_mov_b64 s[2:3], -1
	s_and_b64 vcc, exec, s[4:5]
	s_cbranch_vccz .LBB0_1737
	s_andn2_b64 vcc, exec, s[0:1]
	s_cbranch_vccnz .LBB0_1736
	s_cmpk_lt_i32 s70, 0x100
	s_waitcnt vmcnt(0)
	s_barrier
	s_cbranch_scc1 .LBB0_1702
	s_lshl_b32 s18, s30, 3
	s_lshl_b32 s8, s70, 3
	s_cbranch_execz .LBB0_1703
	s_branch .LBB0_1722

.LBB0_1755:
	s_cmp_lg_u32 s99, 1
	s_cbranch_scc1 .Lp6_end
	s_mov_b32 s99, 2
	s_waitcnt vmcnt(0) lgkmcnt(0)
	s_barrier
	s_branch .Lp6_G

.LBB0_1873:
	s_cmp_lt_i32 s94, 9
	s_cselect_b64 s[6:7], -1, 0
	s_and_b64 s[0:1], s[6:7], s[0:1]
	s_andn2_b64 vcc, exec, s[0:1]
	s_cbranch_vccnz .LBB0_1918
	s_mov_b32 s99, 0
.Lp8_R:
	s_load_dword s24, s[68:69], 0xe0
	s_cmpk_gt_i32 s70, 0x21f
	v_readfirstlane_b32 s25, v0
	s_cbranch_scc1 .LBB0_1886
	s_cmp_lg_u32 s99, 0
	s_cbranch_scc1 .Lp8_G
	s_cmp_lt_i32 s70, 32
	s_cbranch_scc1 .Lp8_G
	s_bitcmp1_b32 s70, 3
	s_cbranch_scc0 .Lp8_G
	s_mov_b32 s99, 1
	s_branch .LBB0_1886
.Lp8_G:
	s_add_u32 s26, s92, 0xdf05000
	s_addc_u32 s27, s93, 0
	v_lshlrev_b32_e32 v1, 4, v0
	s_add_u32 s28, s92, 0x1704000
	v_or_b32_e32 v10, 0x2000, v1
	s_addc_u32 s29, s93, 0
	v_lshrrev_b32_e32 v2, 7, v10
	v_bfe_u32 v13, v0, 2, 4
	s_movk_i32 s0, 0x70
	s_ashr_i32 s31, s70, 31
	v_and_or_b32 v2, v2, s0, v13
	s_lshr_b32 s0, s31, 29
	s_add_i32 s0, s70, s0
	s_lshr_b32 s4, s25, 6
	s_ashr_i32 s2, s0, 3
	s_and_b32 s0, s0, -8
	s_lshr_b32 s1, s25, 8
	s_lshl_b32 s30, s4, 10
	s_sub_i32 s0, s70, s0
	s_cmp_lt_i32 s0, 0
	s_movk_i32 s33, 0x45
	s_cselect_b32 s3, s33, 0x44
	s_mul_i32 s0, s3, s0
	s_add_i32 s0, s0, s2
	s_ashr_i32 s2, s0, 31
	s_lshr_b32 s2, s2, 26
	s_add_i32 s2, s0, s2
	s_ashr_i32 s3, s2, 6
	s_lshl_b32 s5, s3, 3
	s_sub_i32 s3, 0x44, s5
	s_min_u32 s8, s3, 8
	s_andn2_b32 s2, s2, 63
	v_and_b32_e32 v3, 32, v0
	s_sub_i32 s9, s0, s2
	v_cvt_f32_ubyte0_e32 v4, s8
	v_bitop3_b32 v11, v1, v3, 48 bitop3:0x6c
	v_and_b32_e32 v12, 64, v0
	v_cvt_f32_i32_e32 v3, s9
	v_rcp_iflag_f32_e32 v5, v4
	v_or_b32_e32 v1, v11, v12
	s_waitcnt vmcnt(0)
	v_lshl_or_b32 v130, v2, 12, v1
	v_lshrrev_b32_e32 v2, 3, v0
	v_and_or_b32 v2, v2, 48, v13
	v_lshl_or_b32 v132, v2, 12, v1
	v_mul_f32_e32 v1, v3, v5
	v_trunc_f32_e32 v1, v1
	v_fma_f32 v2, -v1, v4, v3
	v_cvt_i32_f32_e32 v1, v1
	s_ashr_i32 s0, s9, 30
	s_or_b32 s0, s0, 1
	v_cmp_ge_f32_e64 s[2:3], |v2|, v4
	s_and_b64 s[2:3], s[2:3], exec
	s_cselect_b32 s0, s0, 0
	v_readfirstlane_b32 s2, v1
	s_add_i32 s0, s2, s0
	s_mul_i32 s2, s0, s8
	s_sub_i32 s2, s9, s2
	s_sext_i32_i8 s2, s2
	s_add_i32 s12, s5, s2
	s_ashr_i32 s13, s12, 31
	s_bfe_i64 s[8:9], s[0:1], 0x80000
	s_lshl_b64 s[2:3], s[12:13], 20
	s_lshl_b64 s[8:9], s[8:9], 20
	s_add_u32 s20, s28, s8
	s_addc_u32 s21, s29, s9
	s_add_i32 s13, s30, 0
	s_add_i32 m0, s13, 0x10000
	v_mov_b32_e32 v133, 0
	global_load_lds_dwordx4 v132, s[20:21]
	s_add_i32 m0, s13, 0x12000
	s_add_u32 s18, s26, s2
	global_load_lds_dwordx4 v130, s[20:21]
	s_addc_u32 s19, s27, s3
	s_mov_b32 m0, s13
	s_add_i32 s34, s13, 0x2000
	global_load_lds_dwordx4 v132, s[18:19]
	s_mov_b32 m0, s34
	s_add_u32 s2, s20, 0x80000
	global_load_lds_dwordx4 v130, s[18:19]
	s_addc_u32 s3, s21, 0
	s_add_i32 m0, s13, 0x14000
	v_mov_b32_e32 v131, v133
	global_load_lds_dwordx4 v132, s[2:3]
	s_add_i32 m0, s13, 0x16000
	s_mov_b32 s37, 0
	global_load_lds_dwordx4 v130, s[2:3]
	s_add_u32 s2, s18, 0x80000
	s_addc_u32 s3, s19, 0
	s_add_i32 s35, s13, 0x4000
	s_mov_b32 m0, s35
	s_add_i32 s36, s13, 0x6000
	global_load_lds_dwordx4 v132, s[2:3]
	s_mov_b32 m0, s36
	v_lshl_add_u64 v[8:9], s[20:21], 0, v[132:133]
	global_load_lds_dwordx4 v130, s[2:3]
	v_lshl_add_u64 v[6:7], s[20:21], 0, v[130:131]
	v_lshl_add_u64 v[4:5], s[18:19], 0, v[132:133]
	s_cmp_lg_u32 s1, 1
	v_lshl_add_u64 v[2:3], s[18:19], 0, v[130:131]
	s_cbranch_scc1 .LBB0_1877
	s_barrier

.LBB0_1886:
	s_cmp_eq_u32 s99, 2
	s_cbranch_scc1 .LBB0_1918
	s_waitcnt lgkmcnt(0)
	s_cmpk_lg_i32 s24, 0x100
	s_cselect_b64 s[0:1], -1, 0
	s_cmp_lt_i32 s70, 32
	s_cselect_b64 s[2:3], -1, 0
	s_or_b64 s[4:5], s[2:3], s[0:1]
	s_mov_b64 s[2:3], -1
	s_and_b64 vcc, exec, s[4:5]
	s_cbranch_vccz .LBB0_1903
	s_andn2_b64 vcc, exec, s[0:1]
	s_cbranch_vccnz .LBB0_1902
	v_lshl_or_b32 v1, s70, 3, v187
	s_movk_i32 s0, 0x5f80
	v_cmp_gt_i32_e32 vcc, s0, v1
	s_waitcnt vmcnt(0)
	s_barrier
	s_and_saveexec_b64 s[8:9], vcc
	s_cbranch_execz .LBB0_1901
	v_mov_b32_e32 v3, 0
	v_lshlrev_b32_e32 v2, 3, v250
	s_lshl_b32 s18, s24, 3
	v_lshl_add_u32 v9, v187, 13, 0
	v_lshlrev_b32_e32 v8, 2, v250
	v_lshl_add_u64 v[4:5], s[92:93], 0, v[2:3]
	v_lshlrev_b32_e32 v2, 7, v250
	s_mov_b64 s[0:1], 0x5184000
	v_lshlrev_b32_e32 v6, 4, v250
	s_add_u32 s10, s90, 0xd478000
	v_add_u32_e32 v13, v9, v2
	v_lshlrev_b32_e32 v2, 2, v8
	v_mbcnt_lo_u32_b32 v8, -1, 0
	v_lshl_add_u64 v[4:5], v[4:5], 0, s[0:1]
	v_add_u32_e32 v10, v9, v6
	v_mov_b32_e32 v7, v3
	v_cmp_eq_u32_e64 s[0:1], 0, v250
	s_addc_u32 s11, s91, 0
	s_mov_b64 s[12:13], 0
	s_movk_i32 s19, 0x4000
	v_mov_b32_e32 v11, 0x6000
	v_mov_b32_e32 v12, 0x4000
	s_movk_i32 s20, 0x7fff
	s_mov_b32 s21, 0x807f
	s_mov_b64 s[14:15], 0x4000
	s_movk_i32 s22, 0x5000
	s_movk_i32 s23, 0x1000
	s_movk_i32 s24, 0x3fff
	s_mov_b32 s25, 0xf800000
	v_mov_b32_e32 v14, 0x260
	s_mov_b32 s26, 0xda24260
	s_mov_b32 s27, 0xc0c00000
	s_movk_i32 s28, 0x5f7f
	v_mbcnt_hi_u32_b32 v15, -1, v8
	v_mov_b32_e32 v16, 0x40c00000
	v_mov_b32_e32 v17, 0x5204000
	v_mov_b32_e32 v18, 0x9204000
	v_mov_b32_e32 v19, 0x27835000
	v_mov_b32_e32 v20, 0x27935000
	s_branch .LBB0_1892
